# P5 epilogue: 8 per-row sum-of-squares loads batched at the top, counted vmcnt so stores stay in flight
# speedup vs baseline: 1.0218x; 1.0053x over previous
.LBB0_1052:
	v_lshl_add_u32 v144, s0, 8, v148
	v_ashrrev_i32_e32 v145, 31, v144
	v_lshl_add_u64 v[146:147], v[144:145], 2, s[54:55]
	global_load_dword v145, v[146:147], off
	global_load_dword v247, v[146:147], off offset:64
	global_load_dword v248, v[146:147], off offset:128
	global_load_dword v249, v[146:147], off offset:192
	global_load_dword v250, v[146:147], off offset:512
	global_load_dword v251, v[146:147], off offset:576
	global_load_dword v252, v[146:147], off offset:640
	global_load_dword v253, v[146:147], off offset:704
	v_lshl_or_b32 v156, s1, 7, v150
	v_readlane_b32 s0, v246, 26
	v_mov_b32_e32 v161, v114
	v_mov_b32_e32 v114, v123
	v_readlane_b32 s1, v246, 27
	v_mov_b32_e32 v158, v124
	v_mov_b32_e32 v159, v116
	v_mov_b32_e32 v116, v125
	v_mov_b32_e32 v124, v126
	v_mov_b32_e32 v125, v118
	v_mov_b32_e32 v118, v127
	v_mov_b32_e32 v126, v120
	v_mov_b32_e32 v127, v112
	v_mov_b32_e32 v112, v121
	v_mov_b32_e32 v160, v122
	v_mov_b64_e32 v[120:121], s[0:1]
	v_ashrrev_i32_e32 v157, 31, v156
	v_or_b32_e32 v164, 16, v144
	v_mad_i64_i32 v[162:163], s[0:1], v144, s44, v[120:121]
	v_lshlrev_b64 v[122:123], 1, v[156:157]
	v_ashrrev_i32_e32 v165, 31, v164
	v_lshl_add_u64 v[156:157], v[162:163], 0, v[122:123]
	v_lshl_add_u64 v[162:163], v[164:165], 2, s[54:55]
	s_waitcnt vmcnt(7)
	v_fmamk_f32 v145, v145, 0x3a800000, v154
	v_mul_f32_e32 v155, 0x4b800000, v145
	v_cmp_gt_f32_e32 vcc, s43, v145
	s_nop 1
	v_cndmask_b32_e32 v145, v145, v155, vcc
	v_rsq_f32_e32 v145, v145
	s_nop 0
	v_mul_f32_e32 v155, 0x45800000, v145
	v_cndmask_b32_e32 v166, v145, v155, vcc
	v_pk_mul_f32 v[114:115], v[114:115], v[166:167] op_sel_hi:[1,0]
	v_pk_mul_f32 v[158:159], v[158:159], v[166:167] op_sel_hi:[1,0]
	v_pk_mul_f32 v[116:117], v[116:117], v[166:167] op_sel_hi:[1,0]
	v_pk_mul_f32 v[124:125], v[124:125], v[166:167] op_sel_hi:[1,0]
	v_pk_mul_f32 v[118:119], v[118:119], v[166:167] op_sel_hi:[1,0]
	v_pk_mul_f32 v[126:127], v[126:127], v[166:167] op_sel_hi:[1,0]
	v_pk_mul_f32 v[112:113], v[112:113], v[166:167] op_sel_hi:[1,0]
	v_pk_mul_f32 v[160:161], v[160:161], v[166:167] op_sel_hi:[1,0]
	v_mul_f32_e32 v170, 0xbfb8aa3b, v115
	v_mul_f32_e32 v145, 0xbfb8aa3b, v159
	v_mul_f32_e32 v155, 0xbfb8aa3b, v117
	v_mul_f32_e32 v165, 0xbfb8aa3b, v125
	v_mul_f32_e32 v166, 0xbfb8aa3b, v119
	v_mul_f32_e32 v167, 0xbfb8aa3b, v127
	v_mul_f32_e32 v168, 0xbfb8aa3b, v113
	v_mul_f32_e32 v169, 0xbfb8aa3b, v161
	v_exp_f32_e32 v170, v170
	v_exp_f32_e32 v145, v145
	v_exp_f32_e32 v155, v155
	v_exp_f32_e32 v165, v165
	v_exp_f32_e32 v166, v166
	v_exp_f32_e32 v167, v167
	v_exp_f32_e32 v168, v168
	v_exp_f32_e32 v169, v169
	v_add_f32_e32 v170, 1.0, v170
	v_add_f32_e32 v145, 1.0, v145
	v_add_f32_e32 v155, 1.0, v155
	v_add_f32_e32 v165, 1.0, v165
	v_add_f32_e32 v166, 1.0, v166
	v_add_f32_e32 v167, 1.0, v167
	v_add_f32_e32 v168, 1.0, v168
	v_add_f32_e32 v169, 1.0, v169
	v_rcp_f32_e32 v170, v170
	v_rcp_f32_e32 v145, v145
	v_rcp_f32_e32 v155, v155
	v_rcp_f32_e32 v165, v165
	v_rcp_f32_e32 v166, v166
	v_rcp_f32_e32 v167, v167
	v_rcp_f32_e32 v168, v168
	v_rcp_f32_e32 v169, v169
	v_mul_f32_e32 v115, v115, v170
	v_mul_f32_e32 v145, v159, v145
	v_mul_f32_e32 v117, v117, v155
	v_mul_f32_e32 v125, v125, v165
	v_mul_f32_e32 v119, v119, v166
	v_mul_f32_e32 v127, v127, v167
	v_mul_f32_e32 v113, v113, v168
	v_mul_f32_e32 v155, v161, v169
	v_mul_f32_e32 v115, v114, v115
	v_mul_f32_e32 v145, v158, v145
	v_mul_f32_e32 v116, v116, v117
	v_mul_f32_e32 v117, v124, v125
	v_mul_f32_e32 v118, v118, v119
	v_mul_f32_e32 v119, v126, v127
	v_mul_f32_e32 v124, v112, v113
	v_mul_f32_e32 v125, v160, v155
	v_cvt_pk_bf16_f32 v112, v145, v116
	v_cvt_pk_bf16_f32 v113, v117, v118
	v_cvt_pk_bf16_f32 v114, v119, v124
	v_cvt_pk_bf16_f32 v115, v125, v115
	global_store_dwordx4 v[156:157], v[112:115], off
	s_nop 0
	s_nop 0
	v_mov_b32_e32 v113, v100
	v_mov_b32_e32 v100, v109
	v_mov_b32_e32 v109, v102
	v_mov_b32_e32 v102, v111
	v_mov_b32_e32 v111, v96
	v_mov_b32_e32 v96, v105
	v_mov_b32_e32 v105, v98
	v_mov_b32_e32 v98, v107
	v_mov_b32_e32 v112, v108
	v_mov_b32_e32 v108, v110
	v_mov_b32_e32 v110, v104
	v_mov_b32_e32 v104, v106
	v_or_b32_e32 v106, 32, v144
	v_mad_i64_i32 v[114:115], s[0:1], v164, s44, v[120:121]
	v_lshl_add_u64 v[114:115], v[114:115], 0, v[122:123]
	s_waitcnt vmcnt(7)
	v_mov_b32_e32 v116, v247
	v_fmamk_f32 v107, v116, 0x3a800000, v154
	v_mul_f32_e32 v116, 0x4b800000, v107
	v_cmp_gt_f32_e32 vcc, s43, v107
	s_nop 1
	v_cndmask_b32_e32 v107, v107, v116, vcc
	v_rsq_f32_e32 v118, v107
	v_ashrrev_i32_e32 v107, 31, v106
	v_lshl_add_u64 v[116:117], v[106:107], 2, s[54:55]
	v_mul_f32_e32 v107, 0x45800000, v118
	v_cndmask_b32_e32 v118, v118, v107, vcc
	v_pk_mul_f32 v[98:99], v[98:99], v[118:119] op_sel_hi:[1,0]
	v_pk_mul_f32 v[112:113], v[112:113], v[118:119] op_sel_hi:[1,0]
	v_pk_mul_f32 v[100:101], v[100:101], v[118:119] op_sel_hi:[1,0]
	v_pk_mul_f32 v[108:109], v[108:109], v[118:119] op_sel_hi:[1,0]
	v_pk_mul_f32 v[102:103], v[102:103], v[118:119] op_sel_hi:[1,0]
	v_pk_mul_f32 v[110:111], v[110:111], v[118:119] op_sel_hi:[1,0]
	v_pk_mul_f32 v[96:97], v[96:97], v[118:119] op_sel_hi:[1,0]
	v_pk_mul_f32 v[104:105], v[104:105], v[118:119] op_sel_hi:[1,0]
	v_mul_f32_e32 v145, 0xbfb8aa3b, v99
	v_mul_f32_e32 v107, 0xbfb8aa3b, v113
	v_mul_f32_e32 v118, 0xbfb8aa3b, v101
	v_mul_f32_e32 v119, 0xbfb8aa3b, v109
	v_mul_f32_e32 v124, 0xbfb8aa3b, v103
	v_mul_f32_e32 v125, 0xbfb8aa3b, v111
	v_mul_f32_e32 v126, 0xbfb8aa3b, v97
	v_mul_f32_e32 v127, 0xbfb8aa3b, v105
	v_exp_f32_e32 v145, v145
	v_exp_f32_e32 v107, v107
	v_exp_f32_e32 v118, v118
	v_exp_f32_e32 v119, v119
	v_exp_f32_e32 v124, v124
	v_exp_f32_e32 v125, v125
	v_exp_f32_e32 v126, v126
	v_exp_f32_e32 v127, v127
	v_add_f32_e32 v145, 1.0, v145
	v_add_f32_e32 v107, 1.0, v107
	v_add_f32_e32 v118, 1.0, v118
	v_add_f32_e32 v119, 1.0, v119
	v_add_f32_e32 v124, 1.0, v124
	v_add_f32_e32 v125, 1.0, v125
	v_add_f32_e32 v126, 1.0, v126
	v_add_f32_e32 v127, 1.0, v127
	v_rcp_f32_e32 v145, v145
	v_rcp_f32_e32 v107, v107
	v_rcp_f32_e32 v118, v118
	v_rcp_f32_e32 v119, v119
	v_rcp_f32_e32 v124, v124
	v_rcp_f32_e32 v125, v125
	v_rcp_f32_e32 v126, v126
	v_rcp_f32_e32 v127, v127
	v_mul_f32_e32 v99, v99, v145
	v_mul_f32_e32 v107, v113, v107
	v_mul_f32_e32 v101, v101, v118
	v_mul_f32_e32 v109, v109, v119
	v_mul_f32_e32 v103, v103, v124
	v_mul_f32_e32 v111, v111, v125
	v_mul_f32_e32 v97, v97, v126
	v_mul_f32_e32 v105, v105, v127
	v_mul_f32_e32 v99, v98, v99
	v_mul_f32_e32 v107, v112, v107
	v_mul_f32_e32 v100, v100, v101
	v_mul_f32_e32 v101, v108, v109
	v_mul_f32_e32 v102, v102, v103
	v_mul_f32_e32 v103, v110, v111
	v_mul_f32_e32 v108, v96, v97
	v_mul_f32_e32 v104, v104, v105
	v_cvt_pk_bf16_f32 v96, v107, v100
	v_cvt_pk_bf16_f32 v97, v101, v102
	v_cvt_pk_bf16_f32 v98, v103, v108
	v_cvt_pk_bf16_f32 v99, v104, v99
	global_store_dwordx4 v[114:115], v[96:99], off
	s_nop 0
	s_nop 0
	v_mov_b32_e32 v97, v84
	v_mov_b32_e32 v84, v93
	v_mov_b32_e32 v93, v86
	v_mov_b32_e32 v86, v95
	v_mov_b32_e32 v95, v80
	v_mov_b32_e32 v80, v89
	v_mov_b32_e32 v89, v82
	v_mov_b32_e32 v82, v91
	v_mov_b32_e32 v96, v92
	v_mov_b32_e32 v92, v94
	v_mov_b32_e32 v94, v88
	v_mov_b32_e32 v88, v90
	v_or_b32_e32 v90, 48, v144
	v_mad_i64_i32 v[98:99], s[0:1], v106, s44, v[120:121]
	v_lshl_add_u64 v[98:99], v[98:99], 0, v[122:123]
	s_waitcnt vmcnt(7)
	v_mov_b32_e32 v100, v248
	v_fmamk_f32 v91, v100, 0x3a800000, v154
	v_mul_f32_e32 v100, 0x4b800000, v91
	v_cmp_gt_f32_e32 vcc, s43, v91
	s_nop 1
	v_cndmask_b32_e32 v91, v91, v100, vcc
	v_rsq_f32_e32 v102, v91
	v_ashrrev_i32_e32 v91, 31, v90
	v_lshl_add_u64 v[100:101], v[90:91], 2, s[54:55]
	v_mul_f32_e32 v91, 0x45800000, v102
	v_cndmask_b32_e32 v102, v102, v91, vcc
	v_pk_mul_f32 v[82:83], v[82:83], v[102:103] op_sel_hi:[1,0]
	v_pk_mul_f32 v[96:97], v[96:97], v[102:103] op_sel_hi:[1,0]
	v_pk_mul_f32 v[84:85], v[84:85], v[102:103] op_sel_hi:[1,0]
	v_pk_mul_f32 v[92:93], v[92:93], v[102:103] op_sel_hi:[1,0]
	v_pk_mul_f32 v[86:87], v[86:87], v[102:103] op_sel_hi:[1,0]
	v_pk_mul_f32 v[94:95], v[94:95], v[102:103] op_sel_hi:[1,0]
	v_pk_mul_f32 v[80:81], v[80:81], v[102:103] op_sel_hi:[1,0]
	v_pk_mul_f32 v[88:89], v[88:89], v[102:103] op_sel_hi:[1,0]
	v_mul_f32_e32 v108, 0xbfb8aa3b, v83
	v_mul_f32_e32 v91, 0xbfb8aa3b, v97
	v_mul_f32_e32 v102, 0xbfb8aa3b, v85
	v_mul_f32_e32 v103, 0xbfb8aa3b, v93
	v_mul_f32_e32 v104, 0xbfb8aa3b, v87
	v_mul_f32_e32 v105, 0xbfb8aa3b, v95
	v_mul_f32_e32 v106, 0xbfb8aa3b, v81
	v_mul_f32_e32 v107, 0xbfb8aa3b, v89
	v_exp_f32_e32 v108, v108
	v_exp_f32_e32 v91, v91
	v_exp_f32_e32 v102, v102
	v_exp_f32_e32 v103, v103
	v_exp_f32_e32 v104, v104
	v_exp_f32_e32 v105, v105
	v_exp_f32_e32 v106, v106
	v_exp_f32_e32 v107, v107
	v_add_f32_e32 v108, 1.0, v108
	v_add_f32_e32 v91, 1.0, v91
	v_add_f32_e32 v102, 1.0, v102
	v_add_f32_e32 v103, 1.0, v103
	v_add_f32_e32 v104, 1.0, v104
	v_add_f32_e32 v105, 1.0, v105
	v_add_f32_e32 v106, 1.0, v106
	v_add_f32_e32 v107, 1.0, v107
	v_rcp_f32_e32 v108, v108
	v_rcp_f32_e32 v91, v91
	v_rcp_f32_e32 v102, v102
	v_rcp_f32_e32 v103, v103
	v_rcp_f32_e32 v104, v104
	v_rcp_f32_e32 v105, v105
	v_rcp_f32_e32 v106, v106
	v_rcp_f32_e32 v107, v107
	v_mul_f32_e32 v83, v83, v108
	v_mul_f32_e32 v91, v97, v91
	v_mul_f32_e32 v85, v85, v102
	v_mul_f32_e32 v93, v93, v103
	v_mul_f32_e32 v87, v87, v104
	v_mul_f32_e32 v95, v95, v105
	v_mul_f32_e32 v81, v81, v106
	v_mul_f32_e32 v89, v89, v107
	v_mul_f32_e32 v83, v82, v83
	v_mul_f32_e32 v91, v96, v91
	v_mul_f32_e32 v84, v84, v85
	v_mul_f32_e32 v85, v92, v93
	v_mul_f32_e32 v86, v86, v87
	v_mul_f32_e32 v87, v94, v95
	v_mul_f32_e32 v92, v80, v81
	v_mul_f32_e32 v88, v88, v89
	v_cvt_pk_bf16_f32 v80, v91, v84
	v_cvt_pk_bf16_f32 v81, v85, v86
	v_cvt_pk_bf16_f32 v82, v87, v92
	v_cvt_pk_bf16_f32 v83, v88, v83
	global_store_dwordx4 v[98:99], v[80:83], off
	s_nop 0
	s_nop 0
	v_mov_b32_e32 v80, v76
	v_mov_b32_e32 v76, v78
	v_mov_b32_e32 v78, v68
	v_mov_b32_e32 v68, v70
	v_mov_b32_e32 v81, v72
	v_mov_b32_e32 v72, v77
	v_mov_b32_e32 v77, v74
	v_mov_b32_e32 v74, v79
	v_mov_b32_e32 v79, v64
	v_mov_b32_e32 v64, v69
	v_mov_b32_e32 v69, v66
	v_mov_b32_e32 v66, v71
	s_waitcnt vmcnt(7)
	v_mov_b32_e32 v82, v249
	v_fmamk_f32 v70, v82, 0x3a800000, v154
	v_mul_f32_e32 v71, 0x4b800000, v70
	v_cmp_gt_f32_e32 vcc, s43, v70
	s_nop 1
	v_cndmask_b32_e32 v70, v70, v71, vcc
	v_rsq_f32_e32 v82, v70
	v_mad_i64_i32 v[70:71], s[0:1], v90, s44, v[120:121]
	v_lshl_add_u64 v[70:71], v[70:71], 0, v[122:123]
	v_mul_f32_e32 v83, 0x45800000, v82
	v_cndmask_b32_e32 v82, v82, v83, vcc
	v_pk_mul_f32 v[66:67], v[66:67], v[82:83] op_sel_hi:[1,0]
	v_pk_mul_f32 v[80:81], v[80:81], v[82:83] op_sel_hi:[1,0]
	v_pk_mul_f32 v[72:73], v[72:73], v[82:83] op_sel_hi:[1,0]
	v_pk_mul_f32 v[76:77], v[76:77], v[82:83] op_sel_hi:[1,0]
	v_pk_mul_f32 v[74:75], v[74:75], v[82:83] op_sel_hi:[1,0]
	v_pk_mul_f32 v[78:79], v[78:79], v[82:83] op_sel_hi:[1,0]
	v_pk_mul_f32 v[64:65], v[64:65], v[82:83] op_sel_hi:[1,0]
	v_pk_mul_f32 v[68:69], v[68:69], v[82:83] op_sel_hi:[1,0]
	v_mul_f32_e32 v89, 0xbfb8aa3b, v67
	v_mul_f32_e32 v82, 0xbfb8aa3b, v81
	v_mul_f32_e32 v83, 0xbfb8aa3b, v73
	v_mul_f32_e32 v84, 0xbfb8aa3b, v77
	v_mul_f32_e32 v85, 0xbfb8aa3b, v75
	v_mul_f32_e32 v86, 0xbfb8aa3b, v79
	v_mul_f32_e32 v87, 0xbfb8aa3b, v65
	v_mul_f32_e32 v88, 0xbfb8aa3b, v69
	v_exp_f32_e32 v89, v89
	v_exp_f32_e32 v82, v82
	v_exp_f32_e32 v83, v83
	v_exp_f32_e32 v84, v84
	v_exp_f32_e32 v85, v85
	v_exp_f32_e32 v86, v86
	v_exp_f32_e32 v87, v87
	v_exp_f32_e32 v88, v88
	v_add_f32_e32 v89, 1.0, v89
	v_add_f32_e32 v82, 1.0, v82
	v_add_f32_e32 v83, 1.0, v83
	v_add_f32_e32 v84, 1.0, v84
	v_add_f32_e32 v85, 1.0, v85
	v_add_f32_e32 v86, 1.0, v86
	v_add_f32_e32 v87, 1.0, v87
	v_add_f32_e32 v88, 1.0, v88
	v_rcp_f32_e32 v89, v89
	v_rcp_f32_e32 v82, v82
	v_rcp_f32_e32 v83, v83
	v_rcp_f32_e32 v84, v84
	v_rcp_f32_e32 v85, v85
	v_rcp_f32_e32 v86, v86
	v_rcp_f32_e32 v87, v87
	v_rcp_f32_e32 v88, v88
	v_mul_f32_e32 v67, v67, v89
	v_mul_f32_e32 v81, v81, v82
	v_mul_f32_e32 v73, v73, v83
	v_mul_f32_e32 v77, v77, v84
	v_mul_f32_e32 v75, v75, v85
	v_mul_f32_e32 v79, v79, v86
	v_mul_f32_e32 v65, v65, v87
	v_mul_f32_e32 v69, v69, v88
	v_mul_f32_e32 v67, v66, v67
	v_mul_f32_e32 v80, v80, v81
	v_mul_f32_e32 v72, v72, v73
	v_mul_f32_e32 v73, v76, v77
	v_mul_f32_e32 v74, v74, v75
	v_mul_f32_e32 v75, v78, v79
	v_mul_f32_e32 v76, v64, v65
	v_mul_f32_e32 v68, v68, v69
	v_cvt_pk_bf16_f32 v64, v80, v72
	v_cvt_pk_bf16_f32 v65, v73, v74
	v_cvt_pk_bf16_f32 v66, v75, v76
	v_cvt_pk_bf16_f32 v67, v68, v67
	global_store_dwordx4 v[70:71], v[64:67], off
	s_nop 0
	s_nop 0
	v_mov_b32_e32 v65, v56
	v_mov_b32_e32 v56, v61
	v_mov_b32_e32 v61, v58
	v_mov_b32_e32 v58, v63
	v_mov_b32_e32 v63, v48
	v_mov_b32_e32 v48, v53
	v_mov_b32_e32 v53, v50
	v_mov_b32_e32 v50, v55
	v_mov_b32_e32 v64, v60
	v_mov_b32_e32 v60, v62
	v_mov_b32_e32 v62, v52
	v_mov_b32_e32 v52, v54
	v_add_u32_e32 v54, 0x80, v144
	s_waitcnt vmcnt(7)
	v_mov_b32_e32 v66, v250
	v_fmamk_f32 v55, v66, 0x3a800000, v154
	v_mul_f32_e32 v66, 0x4b800000, v55
	v_cmp_gt_f32_e32 vcc, s43, v55
	s_nop 1
	v_cndmask_b32_e32 v55, v55, v66, vcc
	v_rsq_f32_e32 v66, v55
	v_mad_i64_i32 v[54:55], s[0:1], v54, s44, v[120:121]
	v_lshl_add_u64 v[54:55], v[54:55], 0, v[122:123]
	v_mul_f32_e32 v67, 0x45800000, v66
	v_cndmask_b32_e32 v66, v66, v67, vcc
	v_pk_mul_f32 v[50:51], v[50:51], v[66:67] op_sel_hi:[1,0]
	v_pk_mul_f32 v[64:65], v[64:65], v[66:67] op_sel_hi:[1,0]
	v_pk_mul_f32 v[56:57], v[56:57], v[66:67] op_sel_hi:[1,0]
	v_pk_mul_f32 v[60:61], v[60:61], v[66:67] op_sel_hi:[1,0]
	v_pk_mul_f32 v[58:59], v[58:59], v[66:67] op_sel_hi:[1,0]
	v_pk_mul_f32 v[62:63], v[62:63], v[66:67] op_sel_hi:[1,0]
	v_pk_mul_f32 v[48:49], v[48:49], v[66:67] op_sel_hi:[1,0]
	v_pk_mul_f32 v[52:53], v[52:53], v[66:67] op_sel_hi:[1,0]
	v_mul_f32_e32 v73, 0xbfb8aa3b, v51
	v_mul_f32_e32 v66, 0xbfb8aa3b, v65
	v_mul_f32_e32 v67, 0xbfb8aa3b, v57
	v_mul_f32_e32 v68, 0xbfb8aa3b, v61
	v_mul_f32_e32 v69, 0xbfb8aa3b, v59
	v_mul_f32_e32 v70, 0xbfb8aa3b, v63
	v_mul_f32_e32 v71, 0xbfb8aa3b, v49
	v_mul_f32_e32 v72, 0xbfb8aa3b, v53
	v_exp_f32_e32 v73, v73
	v_exp_f32_e32 v66, v66
	v_exp_f32_e32 v67, v67
	v_exp_f32_e32 v68, v68
	v_exp_f32_e32 v69, v69
	v_exp_f32_e32 v70, v70
	v_exp_f32_e32 v71, v71
	v_exp_f32_e32 v72, v72
	v_add_f32_e32 v73, 1.0, v73
	v_add_f32_e32 v66, 1.0, v66
	v_add_f32_e32 v67, 1.0, v67
	v_add_f32_e32 v68, 1.0, v68
	v_add_f32_e32 v69, 1.0, v69
	v_add_f32_e32 v70, 1.0, v70
	v_add_f32_e32 v71, 1.0, v71
	v_add_f32_e32 v72, 1.0, v72
	v_rcp_f32_e32 v73, v73
	v_rcp_f32_e32 v66, v66
	v_rcp_f32_e32 v67, v67
	v_rcp_f32_e32 v68, v68
	v_rcp_f32_e32 v69, v69
	v_rcp_f32_e32 v70, v70
	v_rcp_f32_e32 v71, v71
	v_rcp_f32_e32 v72, v72
	v_mul_f32_e32 v51, v51, v73
	v_mul_f32_e32 v65, v65, v66
	v_mul_f32_e32 v57, v57, v67
	v_mul_f32_e32 v61, v61, v68
	v_mul_f32_e32 v59, v59, v69
	v_mul_f32_e32 v63, v63, v70
	v_mul_f32_e32 v49, v49, v71
	v_mul_f32_e32 v53, v53, v72
	v_mul_f32_e32 v51, v50, v51
	v_mul_f32_e32 v64, v64, v65
	v_mul_f32_e32 v56, v56, v57
	v_mul_f32_e32 v57, v60, v61
	v_mul_f32_e32 v58, v58, v59
	v_mul_f32_e32 v59, v62, v63
	v_mul_f32_e32 v60, v48, v49
	v_mul_f32_e32 v52, v52, v53
	v_cvt_pk_bf16_f32 v48, v64, v56
	v_cvt_pk_bf16_f32 v49, v57, v58
	v_cvt_pk_bf16_f32 v50, v59, v60
	v_cvt_pk_bf16_f32 v51, v52, v51
	global_store_dwordx4 v[54:55], v[48:51], off
	s_nop 0
	s_nop 0
	v_mov_b32_e32 v49, v40
	v_mov_b32_e32 v40, v45
	v_mov_b32_e32 v45, v42
	v_mov_b32_e32 v42, v47
	v_mov_b32_e32 v47, v32
	v_mov_b32_e32 v32, v37
	v_mov_b32_e32 v37, v34
	v_mov_b32_e32 v34, v39
	v_mov_b32_e32 v48, v44
	v_mov_b32_e32 v44, v46
	v_mov_b32_e32 v46, v36
	v_mov_b32_e32 v36, v38
	v_add_u32_e32 v38, 0x90, v144
	s_waitcnt vmcnt(7)
	v_mov_b32_e32 v50, v251
	v_fmamk_f32 v39, v50, 0x3a800000, v154
	v_mul_f32_e32 v50, 0x4b800000, v39
	v_cmp_gt_f32_e32 vcc, s43, v39
	s_nop 1
	v_cndmask_b32_e32 v39, v39, v50, vcc
	v_rsq_f32_e32 v50, v39
	v_mad_i64_i32 v[38:39], s[0:1], v38, s44, v[120:121]
	v_lshl_add_u64 v[38:39], v[38:39], 0, v[122:123]
	v_mul_f32_e32 v51, 0x45800000, v50
	v_cndmask_b32_e32 v50, v50, v51, vcc
	v_pk_mul_f32 v[34:35], v[34:35], v[50:51] op_sel_hi:[1,0]
	v_pk_mul_f32 v[48:49], v[48:49], v[50:51] op_sel_hi:[1,0]
	v_pk_mul_f32 v[40:41], v[40:41], v[50:51] op_sel_hi:[1,0]
	v_pk_mul_f32 v[44:45], v[44:45], v[50:51] op_sel_hi:[1,0]
	v_pk_mul_f32 v[42:43], v[42:43], v[50:51] op_sel_hi:[1,0]
	v_pk_mul_f32 v[46:47], v[46:47], v[50:51] op_sel_hi:[1,0]
	v_pk_mul_f32 v[32:33], v[32:33], v[50:51] op_sel_hi:[1,0]
	v_pk_mul_f32 v[36:37], v[36:37], v[50:51] op_sel_hi:[1,0]
	v_mul_f32_e32 v57, 0xbfb8aa3b, v35
	v_mul_f32_e32 v50, 0xbfb8aa3b, v49
	v_mul_f32_e32 v51, 0xbfb8aa3b, v41
	v_mul_f32_e32 v52, 0xbfb8aa3b, v45
	v_mul_f32_e32 v53, 0xbfb8aa3b, v43
	v_mul_f32_e32 v54, 0xbfb8aa3b, v47
	v_mul_f32_e32 v55, 0xbfb8aa3b, v33
	v_mul_f32_e32 v56, 0xbfb8aa3b, v37
	v_exp_f32_e32 v57, v57
	v_exp_f32_e32 v50, v50
	v_exp_f32_e32 v51, v51
	v_exp_f32_e32 v52, v52
	v_exp_f32_e32 v53, v53
	v_exp_f32_e32 v54, v54
	v_exp_f32_e32 v55, v55
	v_exp_f32_e32 v56, v56
	v_add_f32_e32 v57, 1.0, v57
	v_add_f32_e32 v50, 1.0, v50
	v_add_f32_e32 v51, 1.0, v51
	v_add_f32_e32 v52, 1.0, v52
	v_add_f32_e32 v53, 1.0, v53
	v_add_f32_e32 v54, 1.0, v54
	v_add_f32_e32 v55, 1.0, v55
	v_add_f32_e32 v56, 1.0, v56
	v_rcp_f32_e32 v57, v57
	v_rcp_f32_e32 v50, v50
	v_rcp_f32_e32 v51, v51
	v_rcp_f32_e32 v52, v52
	v_rcp_f32_e32 v53, v53
	v_rcp_f32_e32 v54, v54
	v_rcp_f32_e32 v55, v55
	v_rcp_f32_e32 v56, v56
	v_mul_f32_e32 v35, v35, v57
	v_mul_f32_e32 v49, v49, v50
	v_mul_f32_e32 v41, v41, v51
	v_mul_f32_e32 v45, v45, v52
	v_mul_f32_e32 v43, v43, v53
	v_mul_f32_e32 v47, v47, v54
	v_mul_f32_e32 v33, v33, v55
	v_mul_f32_e32 v37, v37, v56
	v_mul_f32_e32 v35, v34, v35
	v_mul_f32_e32 v48, v48, v49
	v_mul_f32_e32 v40, v40, v41
	v_mul_f32_e32 v41, v44, v45
	v_mul_f32_e32 v42, v42, v43
	v_mul_f32_e32 v43, v46, v47
	v_mul_f32_e32 v44, v32, v33
	v_mul_f32_e32 v36, v36, v37
	v_cvt_pk_bf16_f32 v32, v48, v40
	v_cvt_pk_bf16_f32 v33, v41, v42
	v_cvt_pk_bf16_f32 v34, v43, v44
	v_cvt_pk_bf16_f32 v35, v36, v35
	global_store_dwordx4 v[38:39], v[32:35], off
	s_nop 0
	s_nop 0
	v_mov_b32_e32 v33, v24
	v_mov_b32_e32 v24, v29
	v_mov_b32_e32 v29, v26
	v_mov_b32_e32 v26, v31
	v_mov_b32_e32 v31, v16
	v_mov_b32_e32 v16, v21
	v_mov_b32_e32 v21, v18
	v_mov_b32_e32 v18, v23
	v_mov_b32_e32 v32, v28
	v_mov_b32_e32 v28, v30
	v_mov_b32_e32 v30, v20
	v_mov_b32_e32 v20, v22
	v_add_u32_e32 v22, 0xa0, v144
	s_waitcnt vmcnt(7)
	v_mov_b32_e32 v34, v252
	v_fmamk_f32 v23, v34, 0x3a800000, v154
	v_mul_f32_e32 v34, 0x4b800000, v23
	v_cmp_gt_f32_e32 vcc, s43, v23
	s_nop 1
	v_cndmask_b32_e32 v23, v23, v34, vcc
	v_rsq_f32_e32 v34, v23
	v_mad_i64_i32 v[22:23], s[0:1], v22, s44, v[120:121]
	v_lshl_add_u64 v[22:23], v[22:23], 0, v[122:123]
	v_mul_f32_e32 v35, 0x45800000, v34
	v_cndmask_b32_e32 v34, v34, v35, vcc
	v_pk_mul_f32 v[18:19], v[18:19], v[34:35] op_sel_hi:[1,0]
	v_pk_mul_f32 v[32:33], v[32:33], v[34:35] op_sel_hi:[1,0]
	v_pk_mul_f32 v[24:25], v[24:25], v[34:35] op_sel_hi:[1,0]
	v_pk_mul_f32 v[28:29], v[28:29], v[34:35] op_sel_hi:[1,0]
	v_pk_mul_f32 v[26:27], v[26:27], v[34:35] op_sel_hi:[1,0]
	v_pk_mul_f32 v[30:31], v[30:31], v[34:35] op_sel_hi:[1,0]
	v_pk_mul_f32 v[16:17], v[16:17], v[34:35] op_sel_hi:[1,0]
	v_pk_mul_f32 v[20:21], v[20:21], v[34:35] op_sel_hi:[1,0]
	v_mul_f32_e32 v41, 0xbfb8aa3b, v19
	v_mul_f32_e32 v34, 0xbfb8aa3b, v33
	v_mul_f32_e32 v35, 0xbfb8aa3b, v25
	v_mul_f32_e32 v36, 0xbfb8aa3b, v29
	v_mul_f32_e32 v37, 0xbfb8aa3b, v27
	v_mul_f32_e32 v38, 0xbfb8aa3b, v31
	v_mul_f32_e32 v39, 0xbfb8aa3b, v17
	v_mul_f32_e32 v40, 0xbfb8aa3b, v21
	v_exp_f32_e32 v41, v41
	v_exp_f32_e32 v34, v34
	v_exp_f32_e32 v35, v35
	v_exp_f32_e32 v36, v36
	v_exp_f32_e32 v37, v37
	v_exp_f32_e32 v38, v38
	v_exp_f32_e32 v39, v39
	v_exp_f32_e32 v40, v40
	v_add_f32_e32 v41, 1.0, v41
	v_add_f32_e32 v34, 1.0, v34
	v_add_f32_e32 v35, 1.0, v35
	v_add_f32_e32 v36, 1.0, v36
	v_add_f32_e32 v37, 1.0, v37
	v_add_f32_e32 v38, 1.0, v38
	v_add_f32_e32 v39, 1.0, v39
	v_add_f32_e32 v40, 1.0, v40
	v_rcp_f32_e32 v41, v41
	v_rcp_f32_e32 v34, v34
	v_rcp_f32_e32 v35, v35
	v_rcp_f32_e32 v36, v36
	v_rcp_f32_e32 v37, v37
	v_rcp_f32_e32 v38, v38
	v_rcp_f32_e32 v39, v39
	v_rcp_f32_e32 v40, v40
	v_mul_f32_e32 v19, v19, v41
	v_mul_f32_e32 v33, v33, v34
	v_mul_f32_e32 v25, v25, v35
	v_mul_f32_e32 v29, v29, v36
	v_mul_f32_e32 v27, v27, v37
	v_mul_f32_e32 v31, v31, v38
	v_mul_f32_e32 v17, v17, v39
	v_mul_f32_e32 v21, v21, v40
	v_mul_f32_e32 v19, v18, v19
	v_mul_f32_e32 v32, v32, v33
	v_mul_f32_e32 v24, v24, v25
	v_mul_f32_e32 v25, v28, v29
	v_mul_f32_e32 v26, v26, v27
	v_mul_f32_e32 v27, v30, v31
	v_mul_f32_e32 v28, v16, v17
	v_mul_f32_e32 v20, v20, v21
	v_cvt_pk_bf16_f32 v16, v32, v24
	v_cvt_pk_bf16_f32 v17, v25, v26
	v_cvt_pk_bf16_f32 v18, v27, v28
	v_cvt_pk_bf16_f32 v19, v20, v19
	global_store_dwordx4 v[22:23], v[16:19], off
	s_nop 0
	s_andn2_b64 vcc, exec, s[4:5]
	v_mov_b32_e32 v17, v8
	v_mov_b32_e32 v8, v13
	v_mov_b32_e32 v13, v10
	v_mov_b32_e32 v10, v15
	v_mov_b32_e32 v15, v0
	v_mov_b32_e32 v0, v5
	v_mov_b32_e32 v5, v2
	v_mov_b32_e32 v2, v7
	v_mov_b32_e32 v16, v12
	v_mov_b32_e32 v12, v14
	v_mov_b32_e32 v14, v4
	v_mov_b32_e32 v4, v6
	v_add_u32_e32 v6, 0xb0, v144
	s_waitcnt vmcnt(7)
	v_mov_b32_e32 v18, v253
	v_fmamk_f32 v7, v18, 0x3a800000, v154
	v_mul_f32_e32 v18, 0x4b800000, v7
	v_cmp_gt_f32_e64 s[0:1], s43, v7
	s_nop 1
	v_cndmask_b32_e64 v7, v7, v18, s[0:1]
	v_rsq_f32_e32 v18, v7
	v_mad_i64_i32 v[6:7], s[2:3], v6, s44, v[120:121]
	v_lshl_add_u64 v[6:7], v[6:7], 0, v[122:123]
	v_mul_f32_e32 v19, 0x45800000, v18
	v_cndmask_b32_e64 v18, v18, v19, s[0:1]
	v_pk_mul_f32 v[2:3], v[2:3], v[18:19] op_sel_hi:[1,0]
	v_pk_mul_f32 v[16:17], v[16:17], v[18:19] op_sel_hi:[1,0]
	v_pk_mul_f32 v[8:9], v[8:9], v[18:19] op_sel_hi:[1,0]
	v_pk_mul_f32 v[12:13], v[12:13], v[18:19] op_sel_hi:[1,0]
	v_pk_mul_f32 v[10:11], v[10:11], v[18:19] op_sel_hi:[1,0]
	v_pk_mul_f32 v[14:15], v[14:15], v[18:19] op_sel_hi:[1,0]
	v_pk_mul_f32 v[0:1], v[0:1], v[18:19] op_sel_hi:[1,0]
	v_pk_mul_f32 v[4:5], v[4:5], v[18:19] op_sel_hi:[1,0]
	v_mul_f32_e32 v25, 0xbfb8aa3b, v3
	v_mul_f32_e32 v18, 0xbfb8aa3b, v17
	v_mul_f32_e32 v19, 0xbfb8aa3b, v9
	v_mul_f32_e32 v20, 0xbfb8aa3b, v13
	v_mul_f32_e32 v21, 0xbfb8aa3b, v11
	v_mul_f32_e32 v22, 0xbfb8aa3b, v15
	v_mul_f32_e32 v23, 0xbfb8aa3b, v1
	v_mul_f32_e32 v24, 0xbfb8aa3b, v5
	v_exp_f32_e32 v25, v25
	v_exp_f32_e32 v18, v18
	v_exp_f32_e32 v19, v19
	v_exp_f32_e32 v20, v20
	v_exp_f32_e32 v21, v21
	v_exp_f32_e32 v22, v22
	v_exp_f32_e32 v23, v23
	v_exp_f32_e32 v24, v24
	v_add_f32_e32 v25, 1.0, v25
	v_add_f32_e32 v18, 1.0, v18
	v_add_f32_e32 v19, 1.0, v19
	v_add_f32_e32 v20, 1.0, v20
	v_add_f32_e32 v21, 1.0, v21
	v_add_f32_e32 v22, 1.0, v22
	v_add_f32_e32 v23, 1.0, v23
	v_add_f32_e32 v24, 1.0, v24
	v_rcp_f32_e32 v25, v25
	v_rcp_f32_e32 v18, v18
	v_rcp_f32_e32 v19, v19
	v_rcp_f32_e32 v20, v20
	v_rcp_f32_e32 v21, v21
	v_rcp_f32_e32 v22, v22
	v_rcp_f32_e32 v23, v23
	v_rcp_f32_e32 v24, v24
	v_mul_f32_e32 v3, v3, v25
	v_mul_f32_e32 v17, v17, v18
	v_mul_f32_e32 v9, v9, v19
	v_mul_f32_e32 v13, v13, v20
	v_mul_f32_e32 v11, v11, v21
	v_mul_f32_e32 v15, v15, v22
	v_mul_f32_e32 v1, v1, v23
	v_mul_f32_e32 v5, v5, v24
	v_mul_f32_e32 v3, v2, v3
	s_mov_b64 s[0:1], -1
	v_mul_f32_e32 v16, v16, v17
	v_mul_f32_e32 v8, v8, v9
	v_mul_f32_e32 v9, v12, v13
	v_mul_f32_e32 v10, v10, v11
	v_mul_f32_e32 v11, v14, v15
	v_mul_f32_e32 v12, v0, v1
	v_mul_f32_e32 v4, v4, v5
	v_cvt_pk_bf16_f32 v0, v16, v8
	v_cvt_pk_bf16_f32 v1, v9, v10
	v_cvt_pk_bf16_f32 v2, v11, v12
	v_cvt_pk_bf16_f32 v3, v4, v3
	global_store_dwordx4 v[6:7], v[0:3], off
	s_cbranch_vccnz .LBB0_1045
	s_andn2_b64 vcc, exec, s[8:9]
	s_cbranch_vccnz .LBB0_1044
	s_barrier
	s_branch .LBB0_1044

	.amdhsa_kernel _ZN2mk14fwd_megakernelENS_6ParamsE
		.amdhsa_group_segment_fixed_size 0
		.amdhsa_private_segment_fixed_size 0
		.amdhsa_kernarg_size 384
		.amdhsa_user_sgpr_count 2
		.amdhsa_user_sgpr_dispatch_ptr 0
		.amdhsa_user_sgpr_queue_ptr 0
		.amdhsa_user_sgpr_kernarg_segment_ptr 1
		.amdhsa_user_sgpr_dispatch_id 0
		.amdhsa_user_sgpr_kernarg_preload_length 0
		.amdhsa_user_sgpr_kernarg_preload_offset 0
		.amdhsa_user_sgpr_private_segment_size 0
		.amdhsa_uses_dynamic_stack 0
		.amdhsa_enable_private_segment 0
		.amdhsa_system_sgpr_workgroup_id_x 1
		.amdhsa_system_sgpr_workgroup_id_y 0
		.amdhsa_system_sgpr_workgroup_id_z 0
		.amdhsa_system_sgpr_workgroup_info 0
		.amdhsa_system_vgpr_workitem_id 2
		.amdhsa_next_free_vgpr 256
		.amdhsa_next_free_sgpr 98
		.amdhsa_accum_offset 256
		.amdhsa_reserve_vcc 1
		.amdhsa_float_round_mode_32 0
		.amdhsa_float_round_mode_16_64 0
		.amdhsa_float_denorm_mode_32 3
		.amdhsa_float_denorm_mode_16_64 3
		.amdhsa_dx10_clamp 1
		.amdhsa_ieee_mode 1
		.amdhsa_fp16_overflow 0
		.amdhsa_tg_split 0
		.amdhsa_exception_fp_ieee_invalid_op 0
		.amdhsa_exception_fp_denorm_src 0
		.amdhsa_exception_fp_ieee_div_zero 0
		.amdhsa_exception_fp_ieee_overflow 0
		.amdhsa_exception_fp_ieee_underflow 0
		.amdhsa_exception_fp_ieee_inexact 0
		.amdhsa_exception_int_div_zero 0
	.end_amdhsa_kernel

amdhsa.kernels:
  - .agpr_count:     0
    .args:
      - .offset:         0
        .size:           128
        .value_kind:     by_value
      - .offset:         128
        .size:           4
        .value_kind:     hidden_block_count_x
      - .offset:         132
        .size:           4
        .value_kind:     hidden_block_count_y
      - .offset:         136
        .size:           4
        .value_kind:     hidden_block_count_z
      - .offset:         140
        .size:           2
        .value_kind:     hidden_group_size_x
      - .offset:         142
        .size:           2
        .value_kind:     hidden_group_size_y
      - .offset:         144
        .size:           2
        .value_kind:     hidden_group_size_z
      - .offset:         146
        .size:           2
        .value_kind:     hidden_remainder_x
      - .offset:         148
        .size:           2
        .value_kind:     hidden_remainder_y
      - .offset:         150
        .size:           2
        .value_kind:     hidden_remainder_z
      - .offset:         168
        .size:           8
        .value_kind:     hidden_global_offset_x
      - .offset:         176
        .size:           8
        .value_kind:     hidden_global_offset_y
      - .offset:         184
        .size:           8
        .value_kind:     hidden_global_offset_z
      - .offset:         192
        .size:           2
        .value_kind:     hidden_grid_dims
      - .offset:         216
        .size:           8
        .value_kind:     hidden_multigrid_sync_arg
      - .offset:         248
        .size:           4
        .value_kind:     hidden_dynamic_lds_size
    .group_segment_fixed_size: 0
    .kernarg_segment_align: 8
    .kernarg_segment_size: 384
    .language:       OpenCL C
    .language_version:
      - 2
      - 0
    .max_flat_workgroup_size: 512
    .name:           _ZN2mk14fwd_megakernelENS_6ParamsE
    .private_segment_fixed_size: 0
    .sgpr_count:     104
    .sgpr_spill_count: 54
    .symbol:         _ZN2mk14fwd_megakernelENS_6ParamsE.kd
    .uniform_work_group_size: 1
    .uses_dynamic_stack: false
    .vgpr_count:     256
    .vgpr_spill_count: 0
    .wavefront_size: 64
